# attention tile loop rewritten: Q fragments kept in VGPRs (no Q LDS reads), K reads pipelined, PV of previous tile interleaved with softmax VALU, scale+bias folded into exp2 argument, saddr LDS-DMA wit
# speedup vs baseline: 1.0483x; 1.0402x over previous
; DI void attn_stage(const bf16_t* kbase, const bf16_t* vbase, unsigned koff, unsigned voff, LAS unsigned char* ldsbuf, int wid) {
; #pragma unroll
;     for (int i = 0; i < 2; ++i) {
;         const char* src = (const char*)kbase + (size_t)(i * 128) * 2;
;         __builtin_amdgcn_global_load_lds((const unsigned*)(src + koff), (LAS unsigned*)(ldsbuf + (wid + 8 * i) * 1024), 16, 0, 0);
;     }
; #pragma unroll
;     for (int i = 0; i < 2; ++i) {
;         const char* src = (const char*)vbase + (size_t)(16 * i * 2048) * 2;
; DI void phase_attn(int wid0, const Params& p, int L, unsigned char* lds, bool dry) {
;     ...
;         { const int row = 4 * wid + (lane >> 4), gsrc = (lane & 15) ^ (row & 7); koff = (unsigned)(row * 2048 + 8 * gsrc) * 2u;
;           const int w5 = (lane & 31) >> 2, kl = (w5 & 3) + 8 * (w5 >> 2) + 4 * (wid >> 2), col = ((2 * wid + (lane >> 5)) & 7) * 32 + (lane & 3) * 8; voff = (unsigned)(kl * 2048 + col) * 2u; }
;         if (G == 256) {
;             if (ui < 8) { const int bh = 8 * ui + (blk & 7), j = blk >> 3; qb = (ui & 1) ? j : 31 - j; b = bh >> 3; hh = bh & 7; }
;             else if (ui == 8 && blk < 8) { meta = true; hh = blk; b = 0; qb = 0; }
;             else break;
;         } else {
;             const int u = blk + ui * G;
;             if (u < 2048) { const int bh = u & 63; qb = 31 - (u >> 6); b = bh >> 3; hh = bh & 7; }
;             else if (u < 2056) { meta = true; hh = u - 2048; b = 0; qb = 0; }
;             else break;
;         }
;         const int qrow0 = meta ? MREG : b * 4096 + 128 * qb, qpos0 = meta ? 0 : 16 + 128 * qb, ntiles = meta ? 1 : 1 + 4 * (qb + 1);
;         if (tid < 130) tab[tid] = (tid < 129) ? biasT[hh * 129 + tid] : -__builtin_inff();
;         int myrow = qrow0 + 32 * rg + r32; if (meta && myrow > MREG + 63) myrow = MREG + 63;
;         const bf16_t* qp = qbuf + (size_t)myrow * 2048 + hh * 256 + psub * 128 + hi * 8;
;         unsigned char* qlds = lds + wid * 8192 + lane * 16;
; #pragma unroll
;         for (int d0 = 0; d0 < 8; ++d0) *(bf16x8*)(qlds + d0 * 1024) = *(const bf16x8*)(qp + d0 * 16);
;         const int wq0 = qpos0 + 32 * rg, qpos = wq0 + r32;
;         const float bfar = biasT[hh * 129 + 128];
;         const bf16_t* kh_ = kbuf + hh * 256; const bf16_t* vh_ = vbuf + hh * 256;
;         attn_stage(kh_ + (size_t)MREG * 2048, vh_ + (size_t)MREG * 2048, koff, voff, ldsl + 65536, wid);
.LBB0_97:
	s_or_b64 exec, exec, s[10:11]
	s_lshl_b32 s40, s73, 12
	s_lshl_b32 s10, s75, 7
	s_add_i32 s9, s40, s10
	s_and_b64 s[6:7], s[76:77], exec
	s_cselect_b32 s71, 0x8000, s9
	s_lshl_b32 s6, s75, 2
	s_add_i32 s9, s6, 5
	s_and_b64 s[6:7], s[76:77], exec
	v_ashrrev_i32_e32 v0, 4, v4
	v_readlane_b32 s7, v245, 61
	v_and_b32_e32 v2, 15, v4
	v_lshrrev_b32_e32 v3, 1, v4
	v_add_u32_e32 v0, s7, v0
	v_bitop3_b32 v2, v0, v2, 15 bitop3:0x6c
	v_lshlrev_b32_e32 v0, 12, v0
	v_lshl_or_b32 v0, v2, 4, v0
	v_lshrrev_b32_e32 v2, 2, v4
	v_and_b32_e32 v3, 8, v3
	v_readlane_b32 s7, v245, 63
	v_and_or_b32 v2, v2, 3, v3
	v_lshlrev_b32_e32 v8, 3, v4
	v_add_u32_e32 v3, s7, v4
	v_readlane_b32 s7, v244, 1
	v_and_b32_e32 v7, 31, v4
	v_and_b32_e32 v3, 0xe0, v3
	v_and_b32_e32 v5, 24, v8
	v_lshl_add_u32 v2, v2, 11, s7
	v_or3_b32 v2, v2, v3, v5
	v_or_b32_e32 v3, s41, v7
	v_or_b32_e32 v3, s71, v3
	v_min_i32_e32 v9, 0x803f, v3
	v_cndmask_b32_e64 v10, v3, v9, s[76:77]
	s_cselect_b32 s6, 1, s9
	v_ashrrev_i32_e32 v11, 31, v10
	s_lshl_b32 s12, s49, 8
	v_lshlrev_b64 v[10:11], 12, v[10:11]
	s_ashr_i32 s13, s12, 31
	v_ashrrev_i32_e32 v6, 5, v4
	v_lshl_add_u64 v[10:11], s[0:1], 0, v[10:11]
	s_lshl_b64 s[78:79], s[12:13], 1
	v_readlane_b32 s12, v244, 5
	v_lshl_add_u64 v[10:11], v[10:11], 0, s[78:79]
	v_readlane_b32 s13, v244, 6
	v_lshlrev_b32_e32 v12, 3, v6
	v_ashrrev_i32_e32 v13, 31, v12
	v_lshl_add_u64 v[10:11], s[12:13], 1, v[10:11]
	v_lshl_add_u64 v[14:15], v[12:13], 1, v[10:11]
	global_load_dwordx4 v[248:251], v[14:15], off
	s_ashr_i32 s9, s8, 31
	s_lshl_b64 s[8:9], s[8:9], 2
	v_readlane_b32 s12, v245, 40
	v_lshlrev_b32_e32 v9, 4, v4
	v_readlane_b32 s7, v244, 7
	v_readlane_b32 s13, v245, 41
	s_add_u32 s8, s12, s8
	s_addc_u32 s9, s13, s9
	global_load_dword v176, v1, s[8:9] offset:512
	s_add_u32 s12, s28, s78
	s_addc_u32 s13, s29, s79
	s_mov_b64 s[84:85], s[12:13]
	v_readlane_b32 s8, v245, 38
	v_readlane_b32 s9, v245, 39
	s_add_u32 s8, s8, s78
	v_readlane_b32 s7, v244, 9
	s_addc_u32 s9, s9, s79
	s_mov_b64 s[86:87], s[8:9]
	v_lshl_add_u64 v[178:179], s[12:13], 0, v[0:1]
	v_mov_b32_e32 v131, v0
	s_mov_b64 s[14:15], 0x8000000
	s_add_i32 s7, s7, 0
	v_lshlrev_b32_e32 v2, 1, v2
	s_add_i32 m0, s7, 0x10000
	s_mov_b64 s[12:13], 0x8000100
	v_mov_b32_e32 v3, v1
	v_lshl_add_u64 v[180:181], s[8:9], 0, v[2:3]
	v_mov_b32_e32 v208, v2
	v_lshl_add_u64 v[2:3], v[180:181], 0, s[14:15]
	s_mov_b64 s[8:9], 0x8010000
	global_load_dwordx4 v[252:255], v[14:15], off offset:32
	global_load_dwordx4 v[200:203], v[14:15], off offset:64
	global_load_dwordx4 v[204:207], v[14:15], off offset:96
	global_load_dwordx4 v[164:167], v[14:15], off offset:128
	global_load_dwordx4 v[168:171], v[14:15], off offset:160
	global_load_dwordx4 v[172:175], v[14:15], off offset:192
	global_load_dwordx4 v[232:235], v[14:15], off offset:224
	v_lshl_add_u64 v[10:11], v[178:179], 0, s[14:15]
	global_load_lds_dwordx4 v[10:11], off
	v_lshl_add_u64 v[10:11], v[178:179], 0, s[12:13]
	s_add_i32 m0, s7, 0x12000
	s_nop 0
	global_load_lds_dwordx4 v[10:11], off
	s_add_i32 m0, s7, 0x14000
	s_nop 0
	global_load_lds_dwordx4 v[2:3], off
	v_lshl_add_u64 v[2:3], v[180:181], 0, s[8:9]
	s_add_i32 m0, s7, 0x16000
	s_mov_b32 s7, 0
	global_load_lds_dwordx4 v[2:3], off
	s_cmp_lt_i32 s6, 1
	s_cbranch_scc1 .LBB0_114
	s_or_b32 s10, s10, 16
	v_lshlrev_b32_e32 v0, 8, v7
	v_bitop3_b32 v2, v6, v4, 1 bitop3:0x78
	s_and_b64 s[8:9], s[76:77], exec
	v_lshl_add_u32 v193, v2, 4, v0
	v_lshlrev_b32_e32 v2, 1, v4
	s_cselect_b32 s39, 0, s10
	v_and_b32_e32 v0, 0xc0, v9
	v_and_b32_e32 v2, 32, v2
	v_readlane_b32 s48, v244, 17
	s_or_b32 s8, s39, s41
	v_and_b32_e32 v3, 0x100, v8
	v_add3_u32 v0, s48, v0, v2
	v_mov_b32_e32 v14, v1
	v_mov_b32_e32 v15, v1
	s_add_i32 s38, s8, 31
	v_and_b32_e32 v192, 0xe0, v9
	v_lshlrev_b32_e32 v194, 2, v6
	v_add_u32_e32 v195, s8, v7
	v_cmp_gt_u32_e64 s[8:9], 32, v4
	v_lshl_add_u32 v196, v7, 2, s2
	v_lshlrev_b32_e32 v16, 4, v6
	v_cmp_gt_i32_e64 s[10:11], 4, v6
	v_cmp_gt_i32_e64 s[18:19], 2, v6
	v_cmp_gt_i32_e64 s[20:21], 0, v6
	v_cmp_gt_i32_e64 s[22:23], -2, v6
	v_add3_u32 v212, v0, v3, v5
	v_mov_b32_e32 v0, v1
	v_mov_b32_e32 v2, v1
	v_mov_b32_e32 v3, v1
	v_mov_b32_e32 v4, v1
	v_mov_b32_e32 v5, v1
	v_mov_b32_e32 v6, v1
	v_mov_b32_e32 v7, v1
	v_mov_b32_e32 v8, v1
	v_mov_b32_e32 v9, v1
	v_mov_b32_e32 v10, v1
	v_mov_b32_e32 v11, v1
	v_mov_b32_e32 v12, v1
	v_mov_b32_e32 v13, v1
	v_mov_b64_e32 v[128:129], v[14:15]
	v_mov_b64_e32 v[112:113], v[14:15]
	v_mov_b64_e32 v[96:97], v[14:15]
	v_mov_b64_e32 v[80:81], v[14:15]
	v_mov_b64_e32 v[64:65], v[14:15]
	v_mov_b64_e32 v[48:49], v[14:15]
	v_mov_b64_e32 v[32:33], v[14:15]
	v_or_b32_e32 v197, 1, v194
	v_or_b32_e32 v198, 2, v194
	v_or_b32_e32 v199, 3, v194
	v_readlane_b32 s48, v244, 19
	v_add_u32_e32 v214, s2, v16
	v_mov_b64_e32 v[126:127], v[12:13]
	v_mov_b64_e32 v[124:125], v[10:11]
	v_mov_b64_e32 v[122:123], v[8:9]
	v_mov_b64_e32 v[120:121], v[6:7]
	v_mov_b64_e32 v[118:119], v[4:5]
	v_mov_b64_e32 v[116:117], v[2:3]
	v_mov_b64_e32 v[114:115], v[0:1]
	v_mov_b64_e32 v[110:111], v[12:13]
	v_mov_b64_e32 v[108:109], v[10:11]
	v_mov_b64_e32 v[106:107], v[8:9]
	v_mov_b64_e32 v[104:105], v[6:7]
	v_mov_b64_e32 v[102:103], v[4:5]
	v_mov_b64_e32 v[100:101], v[2:3]
	v_mov_b64_e32 v[98:99], v[0:1]
	v_mov_b64_e32 v[94:95], v[12:13]
	v_mov_b64_e32 v[92:93], v[10:11]
	v_mov_b64_e32 v[90:91], v[8:9]
	v_mov_b64_e32 v[88:89], v[6:7]
	v_mov_b64_e32 v[86:87], v[4:5]
	v_mov_b64_e32 v[84:85], v[2:3]
	v_mov_b64_e32 v[82:83], v[0:1]
	v_mov_b64_e32 v[78:79], v[12:13]
	v_mov_b64_e32 v[76:77], v[10:11]
	v_mov_b64_e32 v[74:75], v[8:9]
	v_mov_b64_e32 v[72:73], v[6:7]
	v_mov_b64_e32 v[70:71], v[4:5]
	v_mov_b64_e32 v[68:69], v[2:3]
	v_mov_b64_e32 v[66:67], v[0:1]
	v_mov_b64_e32 v[62:63], v[12:13]
	v_mov_b64_e32 v[60:61], v[10:11]
	v_mov_b64_e32 v[58:59], v[8:9]
	v_mov_b64_e32 v[56:57], v[6:7]
	v_mov_b64_e32 v[54:55], v[4:5]
	v_mov_b64_e32 v[52:53], v[2:3]
	v_mov_b64_e32 v[50:51], v[0:1]
	v_mov_b64_e32 v[46:47], v[12:13]
	v_mov_b64_e32 v[44:45], v[10:11]
	v_mov_b64_e32 v[42:43], v[8:9]
	v_mov_b64_e32 v[40:41], v[6:7]
	v_mov_b64_e32 v[38:39], v[4:5]
	v_mov_b64_e32 v[36:37], v[2:3]
	v_mov_b64_e32 v[34:35], v[0:1]
	v_mov_b64_e32 v[30:31], v[12:13]
	v_mov_b64_e32 v[28:29], v[10:11]
	v_mov_b64_e32 v[26:27], v[8:9]
	v_mov_b64_e32 v[24:25], v[6:7]
	v_mov_b64_e32 v[22:23], v[4:5]
	v_mov_b64_e32 v[20:21], v[2:3]
	v_mov_b64_e32 v[18:19], v[0:1]
	v_mov_b64_e32 v[16:17], v[14:15]
	v_cmp_gt_i32_e64 s[12:13], 16, v197
	v_cmp_gt_i32_e64 s[14:15], 16, v198
	v_cmp_gt_i32_e64 s[16:17], 16, v199
	s_waitcnt vmcnt(11)
; DI int crow(int r, int hi) { return (r & 3) + 8 * (r >> 2) + 4 * hi; }
; #define MFMA32(a, b, c) __builtin_amdgcn_mfma_f32_32x32x16_bf16((a), (b), (c), 0, 0, 0)
; DI void phase_attn(int wid0, const Params& p, int L, unsigned char* lds, bool dry) {
;     ...
;         for (int t = 0; t < ntiles; ++t) {
;             asm volatile("s_waitcnt vmcnt(0) lgkmcnt(0)" ::: "memory"); __builtin_amdgcn_s_barrier(); asm volatile("" ::: "memory");
;             if (t + 1 < ntiles) attn_stage(kh_ + (size_t)(b * 4096 + 32 * t) * 2048, vh_ + (size_t)(b * 4096 + 32 * t) * 2048, koff, voff, ldsl + 65536 + ((t + 1) & 1) * 32768, wid);
;             const int kpos0 = (t == 0) ? 0 : 16 + 32 * (t - 1);
;             if (kpos0 <= wq0 + 31) {
;                 const unsigned char* Ks = lds + 65536 + (t & 1) * 32768 + psub * 8192;
;                 f32x16 p0, p0b;
; #pragma unroll
;                 for (int r = 0; r < 16; ++r) { p0[r] = 0.f; p0b[r] = 0.f; }
;                 int swz = (r32 & 6) << 4, kro = r32 * 256 + ((hi ^ (r32 & 1)) << 4); asm volatile("" : "+v"(swz), "+v"(kro));
; #pragma unroll
;                 for (int d0 = 0; d0 < 8; d0 += 2) {
;                     const bf16x8 b0 = *(const bf16x8*)(Ks + kro + ((d0 * 32) ^ swz));
;                     const bf16x8 qf = *(const bf16x8*)(qlds + d0 * 1024);
;                     const bf16x8 b1 = *(const bf16x8*)(Ks + kro + (((d0 + 1) * 32) ^ swz));
;                     const bf16x8 qg = *(const bf16x8*)(qlds + (d0 + 1) * 1024);
;                     p0 = MFMA32(b0, qf, p0);
;                     p0b = MFMA32(b1, qg, p0b);
;                     if (d0 == 2) __builtin_amdgcn_sched_barrier(0);
;                 }
; #pragma unroll
;                 for (int r = 0; r < 16; ++r) p0[r] += p0b[r];
;                 __builtin_amdgcn_sched_barrier(0);
;                 if (t > 0 && wq0 - (kpos0 + 31) >= 128) {
; #pragma unroll
;                     for (int r = 0; r < 16; ++r) p0[r] = fmaf(p0[r], ATT_C, bfar);
;                 } else {
; #pragma unroll
;                     for (int r = 0; r < 16; ++r) {
;                         const int k0i = crow(r, hi);
;                         const int d0v = qpos - (kpos0 + k0i);
;                         const bool v0 = (d0v >= 0) && (t > 0 || k0i < 16);
;                         const int idx = v0 ? (d0v < 128 ? d0v : 128) : 129;
;                         p0[r] = fmaf(p0[r], ATT_C, tab[idx]);
	v_mov_b32_e32 v182, v176
	v_mov_b32_e32 v183, v176
	s_add_i32 s39, s48, s39
	v_mov_b32_e32 v130, 0
	v_mov_b32_e32 v213, 0xf149f2ca
	s_mov_b32 s66, 0
	s_mov_b32 s100, 0
	s_mov_b32 s101, 0
	v_mov_b32_e32 v132, 0
	v_mov_b32_e32 v133, 0
	v_mov_b32_e32 v134, 0
	v_mov_b32_e32 v135, 0
	v_mov_b32_e32 v136, 0
	v_mov_b32_e32 v137, 0
	v_mov_b32_e32 v138, 0
	v_mov_b32_e32 v139, 0
	v_mov_b64_e32 v[14:15], v[12:13]
	v_mov_b64_e32 v[12:13], v[10:11]
	v_mov_b64_e32 v[10:11], v[8:9]
	v_mov_b64_e32 v[8:9], v[6:7]
	v_mov_b64_e32 v[6:7], v[4:5]
	v_mov_b64_e32 v[4:5], v[2:3]
	v_mov_b64_e32 v[2:3], v[0:1]
	s_mov_b32 s69, 0
.LBB0_99:
	s_waitcnt vmcnt(0) lgkmcnt(0)
	s_barrier
	s_add_i32 s67, s69, 1
	s_cmp_ge_i32 s67, s6
	s_cbranch_scc1 .LBB0_101
	s_add_i32 s80, s40, s7
	s_add_i32 s48, s66, 0x8000
	s_ashr_i32 s81, s80, 31
	s_and_b32 s48, s48, 0x8000
	s_lshl_b64 s[80:81], s[80:81], 12
	s_add_i32 s48, s4, s48
	s_add_u32 s88, s84, s80
	s_addc_u32 s89, s85, s81
	s_add_u32 s90, s88, 0x100
	s_addc_u32 s91, s89, 0
	s_add_u32 s92, s86, s80
	s_addc_u32 s93, s87, s81
	s_add_u32 s94, s92, 0x10000
	s_addc_u32 s95, s93, 0
	s_and_b32 s82, s100, 3
	s_add_i32 s82, s82, 1
	s_cmp_eq_u32 s82, 3
	s_cselect_b32 s82, 0, s82
	s_lshl_b32 s82, s82, 15
	s_add_i32 s82, s4, s82
	s_mov_b32 m0, s48
	s_nop 0
	global_load_lds_dwordx4 v131, s[88:89]
	s_add_i32 m0, s48, 0x2000
	s_nop 0
	global_load_lds_dwordx4 v131, s[90:91]
	s_add_i32 m0, s82, 0x4000
	s_nop 0
	global_load_lds_dwordx4 v208, s[92:93]
	s_add_i32 m0, s82, 0x6000
	s_nop 0
	global_load_lds_dwordx4 v208, s[94:95]
.LBB0_101:
	s_add_i32 s48, s7, -16
	s_cmp_lg_u32 s69, 0
	s_cselect_b32 s48, s48, 0
	s_cmp_gt_i32 s48, s38
	s_cbranch_scc1 .Lattn_skip
	s_and_b32 s68, s66, 0x8000
	s_add_i32 s80, s5, s68
	v_add_u32_e32 v177, s80, v193
	v_add_u32_e32 v215, v177, v192
	ds_read_b128 v[216:219], v215
	v_xad_u32 v215, v192, 32, v177
	ds_read_b128 v[220:223], v215
	v_xad_u32 v215, v192, 64, v177
	ds_read_b128 v[236:239], v215
	s_movk_i32 s80, 0x60
	v_xad_u32 v215, v192, s80, v177
	ds_read_b128 v[240:243], v215
	s_movk_i32 s80, 0x80
	v_xad_u32 v215, v192, s80, v177
	s_waitcnt lgkmcnt(3)
	v_mfma_f32_32x32x16_bf16 v[140:155], v[216:219], v[248:251], 0
	ds_read_b128 v[216:219], v215
	s_movk_i32 s80, 0xa0
	v_xad_u32 v215, v192, s80, v177
	s_waitcnt lgkmcnt(3)
	v_mfma_f32_32x32x16_bf16 v[140:155], v[220:223], v[252:255], v[140:155]
	ds_read_b128 v[220:223], v215
	s_movk_i32 s80, 0xc0
	v_xad_u32 v215, v192, s80, v177
	s_waitcnt lgkmcnt(3)
	v_mfma_f32_32x32x16_bf16 v[140:155], v[236:239], v[200:203], v[140:155]
	ds_read_b128 v[236:239], v215
	s_movk_i32 s80, 0xe0
	v_xad_u32 v215, v192, s80, v177
	s_waitcnt lgkmcnt(3)
	v_mfma_f32_32x32x16_bf16 v[140:155], v[240:243], v[204:207], v[140:155]
	ds_read_b128 v[240:243], v215
	s_waitcnt lgkmcnt(3)
	v_mfma_f32_32x32x16_bf16 v[140:155], v[216:219], v[164:167], v[140:155]
	s_waitcnt lgkmcnt(2)
	v_mfma_f32_32x32x16_bf16 v[140:155], v[220:223], v[168:171], v[140:155]
	s_waitcnt lgkmcnt(1)
	v_mfma_f32_32x32x16_bf16 v[140:155], v[236:239], v[172:175], v[140:155]
	s_waitcnt lgkmcnt(0)
	v_mfma_f32_32x32x16_bf16 v[140:155], v[240:243], v[232:235], v[140:155]
	s_cmp_lg_u32 s69, 0
	s_cselect_b64 s[80:81], -1, 0
	s_cmpk_gt_i32 s39, 0x7f
	s_cselect_b64 s[82:83], -1, 0
	s_and_b64 s[82:83], s[80:81], s[82:83]
	s_andn2_b64 vcc, exec, s[82:83]
	s_cbranch_vccz .Lattn_far
	v_add_u32_e32 v226, s48, v194
	v_sub_u32_e32 v229, v195, v226
	v_sub_u32_e32 v216, v195, v226
	v_cmp_lt_i32_e32 vcc, -1, v216
	s_or_b64 s[82:83], s[10:11], s[80:81]
	v_add_u32_e32 v217, s48, v197
	v_min_i32_e32 v216, 0x80, v216
	s_and_b64 vcc, s[82:83], vcc
	v_sub_u32_e32 v217, v195, v217
	v_cndmask_b32_e32 v216, v187, v216, vcc
	v_cmp_lt_i32_e32 vcc, -1, v217
	s_or_b64 s[82:83], s[12:13], s[80:81]
	v_add_u32_e32 v218, s48, v198
	v_min_i32_e32 v217, 0x80, v217
	s_and_b64 vcc, s[82:83], vcc
	v_sub_u32_e32 v218, v195, v218
	v_cndmask_b32_e32 v217, v187, v217, vcc
	v_cmp_lt_i32_e32 vcc, -1, v218
	s_or_b64 s[82:83], s[14:15], s[80:81]
	v_add_u32_e32 v219, s48, v199
	v_min_i32_e32 v218, 0x80, v218
	s_and_b64 vcc, s[82:83], vcc
	v_sub_u32_e32 v219, v195, v219
	v_cndmask_b32_e32 v218, v187, v218, vcc
	v_cmp_lt_i32_e32 vcc, -1, v219
	s_or_b64 s[82:83], s[16:17], s[80:81]
	v_min_i32_e32 v219, 0x80, v219
	s_and_b64 vcc, s[82:83], vcc
	v_cndmask_b32_e32 v219, v187, v219, vcc
	v_lshl_add_u32 v216, v216, 2, s37
	v_lshl_add_u32 v217, v217, 2, s37
	v_lshl_add_u32 v218, v218, 2, s37
	v_lshl_add_u32 v219, v219, 2, s37
	ds_read_b32 v216, v216
	ds_read_b32 v217, v217
	ds_read_b32 v218, v218
	ds_read_b32 v219, v219
	v_add_u32_e32 v220, -8, v229
	v_cmp_lt_i32_e32 vcc, -1, v220
	s_or_b64 s[82:83], s[18:19], s[80:81]
	v_min_i32_e32 v220, 0x80, v220
	s_and_b64 vcc, s[82:83], vcc
	v_add_u32_e32 v221, -9, v229
	v_cndmask_b32_e32 v220, v187, v220, vcc
	v_cmp_lt_i32_e32 vcc, -1, v221
	v_min_i32_e32 v221, 0x80, v221
	s_and_b64 vcc, s[82:83], vcc
	v_add_u32_e32 v222, -10, v229
	v_cndmask_b32_e32 v221, v187, v221, vcc
	v_cmp_lt_i32_e32 vcc, -1, v222
	v_min_i32_e32 v222, 0x80, v222
	s_and_b64 vcc, s[82:83], vcc
	v_add_u32_e32 v223, -11, v229
	v_cndmask_b32_e32 v222, v187, v222, vcc
	v_cmp_lt_i32_e32 vcc, -1, v223
	v_min_i32_e32 v223, 0x80, v223
	s_and_b64 vcc, s[82:83], vcc
	v_cndmask_b32_e32 v223, v187, v223, vcc
	v_lshl_add_u32 v220, v220, 2, s37
	v_lshl_add_u32 v221, v221, 2, s37
	v_lshl_add_u32 v222, v222, 2, s37
	v_lshl_add_u32 v223, v223, 2, s37
	ds_read_b32 v220, v220
	ds_read_b32 v221, v221
	ds_read_b32 v222, v222
	ds_read_b32 v223, v223
	v_add_u32_e32 v236, -16, v229
	v_cmp_lt_i32_e32 vcc, -1, v236
	s_or_b64 s[82:83], s[20:21], s[80:81]
	v_min_i32_e32 v236, 0x80, v236
; #define LAS __attribute__((address_space(3)))
; DI void phase_attn(int wid0, const Params& p, int L, unsigned char* lds, bool dry) {
;     ...
;                 if (t > 0 && wq0 - (kpos0 + 31) >= 128) {
; #pragma unroll
;                     for (int r = 0; r < 16; ++r) p0[r] = fmaf(p0[r], ATT_C, bfar);
;                 } else {
; #pragma unroll
;                     for (int r = 0; r < 16; ++r) {
;                         const int k0i = crow(r, hi);
;                         const int d0v = qpos - (kpos0 + k0i);
;                         const bool v0 = (d0v >= 0) && (t > 0 || k0i < 16);
;                         const int idx = v0 ? (d0v < 128 ? d0v : 128) : 129;
;                         p0[r] = fmaf(p0[r], ATT_C, tab[idx]);
;                         if ((r & 3) == 3) __builtin_amdgcn_sched_barrier(0);
;                     }
;                 }
;                 __builtin_amdgcn_sched_barrier(0);
;                 float pmax = p0[0];
; #pragma unroll
;                 for (int r = 1; r < 16; ++r) pmax = fmaxf(pmax, p0[r]);
;                 { auto rr = __builtin_amdgcn_permlane32_swap(__float_as_uint(pmax), __float_as_uint(pmax), false, false); pmax = fmaxf(__uint_as_float(rr[0]), __uint_as_float(rr[1])); }
;                 float mn, alpha;
;                 if (__all(pmax - m_reg <= ATT_THR2)) { mn = m_reg; alpha = 1.f; }
;                 else { mn = fmaxf(m_reg, pmax); alpha = __builtin_amdgcn_exp2f(m_reg - mn); m_reg = mn; }
;                 float ps = 0.f;
; #pragma unroll
;                 for (int r = 0; r < 16; ++r) { p0[r] = __builtin_amdgcn_exp2f(p0[r] - mn); ps += p0[r]; }
;                 { auto rr = __builtin_amdgcn_permlane32_swap(__float_as_uint(ps), __float_as_uint(ps), false, false); ps = __uint_as_float(rr[0]) + __uint_as_float(rr[1]); }
;                 l_reg = l_reg * alpha + ps;
;     ...
;                 LAS unsigned char* vbp = ldsl + 65536 + (t & 1) * 32768 + 16384 + v_rd_base(lane);
;                 __builtin_amdgcn_s_setprio(1);
;     ...
;                 {
;                     s16x4 a0, a1, a2, a3, b0_, b1_, b2_, b3_;
;                     PV_RD(0, a0, a1, a2, a3); SB();
;                     PV_RD(1, b0_, b1_, b2_, b3_); SB(); PV_MM(0, a0, a1, a2, a3); SB();
;                     PV_RD(2, a0, a1, a2, a3); SB(); PV_MM(1, b0_, b1_, b2_, b3_); SB();
;                     PV_RD(3, b0_, b1_, b2_, b3_); SB(); PV_MM(2, a0, a1, a2, a3); SB();
	s_and_b64 vcc, s[82:83], vcc
	v_add_u32_e32 v237, 0xffffffef, v229
	v_cndmask_b32_e32 v236, v187, v236, vcc
	v_cmp_lt_i32_e32 vcc, -1, v237
	v_min_i32_e32 v237, 0x80, v237
	s_and_b64 vcc, s[82:83], vcc
	v_add_u32_e32 v238, 0xffffffee, v229
	v_cndmask_b32_e32 v237, v187, v237, vcc
	v_cmp_lt_i32_e32 vcc, -1, v238
	v_min_i32_e32 v238, 0x80, v238
	s_and_b64 vcc, s[82:83], vcc
	v_add_u32_e32 v239, 0xffffffed, v229
	v_cndmask_b32_e32 v238, v187, v238, vcc
	v_cmp_lt_i32_e32 vcc, -1, v239
	v_min_i32_e32 v239, 0x80, v239
	s_and_b64 vcc, s[82:83], vcc
	v_cndmask_b32_e32 v239, v187, v239, vcc
	v_lshl_add_u32 v236, v236, 2, s37
	v_lshl_add_u32 v237, v237, 2, s37
	v_lshl_add_u32 v238, v238, 2, s37
	v_lshl_add_u32 v239, v239, 2, s37
	ds_read_b32 v236, v236
	ds_read_b32 v237, v237
	ds_read_b32 v238, v238
	ds_read_b32 v239, v239
	v_add_u32_e32 v240, 0xffffffe8, v229
	v_cmp_lt_i32_e32 vcc, -1, v240
	s_or_b64 s[80:81], s[22:23], s[80:81]
	v_min_i32_e32 v240, 0x80, v240
	s_and_b64 vcc, s[80:81], vcc
	v_add_u32_e32 v241, 0xffffffe7, v229
	v_cndmask_b32_e32 v240, v187, v240, vcc
	v_cmp_lt_i32_e32 vcc, -1, v241
	v_min_i32_e32 v241, 0x80, v241
	s_and_b64 vcc, s[80:81], vcc
	v_add_u32_e32 v242, 0xffffffe6, v229
	v_cndmask_b32_e32 v241, v187, v241, vcc
	v_cmp_lt_i32_e32 vcc, -1, v242
	v_min_i32_e32 v242, 0x80, v242
	s_and_b64 vcc, s[80:81], vcc
	v_add_u32_e32 v226, 0xffffffe5, v229
	v_cndmask_b32_e32 v242, v187, v242, vcc
	v_cmp_lt_i32_e32 vcc, -1, v226
	v_min_i32_e32 v226, 0x80, v226
	s_and_b64 vcc, s[80:81], vcc
	v_lshl_add_u32 v240, v240, 2, s37
	v_lshl_add_u32 v241, v241, 2, s37
	v_lshl_add_u32 v242, v242, 2, s37
	v_cndmask_b32_e32 v226, v187, v226, vcc
	v_lshl_add_u32 v226, v226, 2, s37
	ds_read_b32 v240, v240
	ds_read_b32 v241, v241
	ds_read_b32 v242, v242
	ds_read_b32 v243, v226
	s_waitcnt lgkmcnt(0)
	v_pk_fma_f32 v[140:141], v[140:141], s[36:37], v[216:217] op_sel_hi:[1,0,1]
	v_pk_fma_f32 v[142:143], v[142:143], s[36:37], v[218:219] op_sel_hi:[1,0,1]
	v_pk_fma_f32 v[144:145], v[144:145], s[36:37], v[220:221] op_sel_hi:[1,0,1]
	v_pk_fma_f32 v[146:147], v[146:147], s[36:37], v[222:223] op_sel_hi:[1,0,1]
	v_pk_fma_f32 v[148:149], v[148:149], s[36:37], v[236:237] op_sel_hi:[1,0,1]
	v_pk_fma_f32 v[150:151], v[150:151], s[36:37], v[238:239] op_sel_hi:[1,0,1]
	v_pk_fma_f32 v[152:153], v[152:153], s[36:37], v[240:241] op_sel_hi:[1,0,1]
	v_pk_fma_f32 v[154:155], v[154:155], s[36:37], v[242:243] op_sel_hi:[1,0,1]
	s_mov_b32 s82, 1.0
	v_mov_b32_e32 v231, 0
	s_branch .Lattn_region
.Lattn_far:
	s_mov_b32 s82, s36
	v_mov_b32_e32 v231, v176
.Lattn_region:
	v_add_u32_e32 v0, s101, v212
	ds_read_b64_tr_b16 v[216:217], v0 offset:16384
	ds_read_b64_tr_b16 v[218:219], v0 offset:20480
	ds_read_b64_tr_b16 v[220:221], v0 offset:24576
	ds_read_b64_tr_b16 v[222:223], v0 offset:28672
	ds_read_b64_tr_b16 v[236:237], v0 offset:16896
	ds_read_b64_tr_b16 v[238:239], v0 offset:20992
	ds_read_b64_tr_b16 v[240:241], v0 offset:25088
	ds_read_b64_tr_b16 v[242:243], v0 offset:29184
	s_waitcnt lgkmcnt(6)
	v_mfma_f32_32x32x16_bf16 v[114:129], v[132:135], v[216:219], v[114:129]
	s_waitcnt lgkmcnt(4)
	v_mfma_f32_32x32x16_bf16 v[114:129], v[136:139], v[220:223], v[114:129]
	v_max3_f32 v226, v140, v141, v142
	v_max3_f32 v226, v226, v143, v144
	v_max3_f32 v226, v226, v145, v146
	v_max3_f32 v226, v226, v147, v148
	v_max3_f32 v226, v226, v149, v150
	v_max3_f32 v226, v226, v151, v152
	v_max3_f32 v226, v226, v153, v154
	ds_read_b64_tr_b16 v[216:217], v0 offset:17408
	ds_read_b64_tr_b16 v[218:219], v0 offset:21504
	ds_read_b64_tr_b16 v[220:221], v0 offset:25600
	ds_read_b64_tr_b16 v[222:223], v0 offset:29696
	s_waitcnt lgkmcnt(6)
	v_mfma_f32_32x32x16_bf16 v[98:113], v[132:135], v[236:239], v[98:113]
	v_max_f32_e32 v226, v226, v155
	v_mov_b32_e32 v227, v226
	s_nop 1
	v_permlane32_swap_b32_e32 v226, v227
	v_max_f32_e32 v226, v226, v227
	v_fma_f32 v226, v226, s82, v231
	v_sub_f32_e32 v227, v226, v213
	s_mov_b32 s48, 0x4138aa3b
	s_waitcnt lgkmcnt(4)
	v_mfma_f32_32x32x16_bf16 v[98:113], v[136:139], v[240:243], v[98:113]
	v_cmp_ge_f32_e32 vcc, s48, v227
	s_cmp_eq_u64 vcc, exec
	v_max_f32_e32 v226, v213, v226
	s_cselect_b64 vcc, -1, 0
	v_sub_f32_e32 v227, v213, v226
	v_cndmask_b32_e32 v213, v226, v213, vcc
	v_sub_f32_e32 v230, v231, v213
	v_fma_f32 v140, v140, s82, v230
	ds_read_b64_tr_b16 v[236:237], v0 offset:17920
	ds_read_b64_tr_b16 v[238:239], v0 offset:22016
	ds_read_b64_tr_b16 v[240:241], v0 offset:26112
	ds_read_b64_tr_b16 v[242:243], v0 offset:30208
	s_waitcnt lgkmcnt(6)
	v_mfma_f32_32x32x16_bf16 v[82:97], v[132:135], v[216:219], v[82:97]
	v_exp_f32_e32 v140, v140
	v_fma_f32 v141, v141, s82, v230
	v_exp_f32_e32 v141, v141
	v_fma_f32 v142, v142, s82, v230
	v_exp_f32_e32 v142, v142
	s_waitcnt lgkmcnt(4)
	v_mfma_f32_32x32x16_bf16 v[82:97], v[136:139], v[220:223], v[82:97]
	v_add_f32_e32 v226, v140, v141
	v_fma_f32 v143, v143, s82, v230
	v_exp_f32_e32 v143, v143
	v_add_f32_e32 v226, v226, v142
	v_fma_f32 v144, v144, s82, v230
	v_exp_f32_e32 v144, v144
	ds_read_b64_tr_b16 v[216:217], v0 offset:18432
	ds_read_b64_tr_b16 v[218:219], v0 offset:22528
	ds_read_b64_tr_b16 v[220:221], v0 offset:26624
	ds_read_b64_tr_b16 v[222:223], v0 offset:30720
	s_waitcnt lgkmcnt(6)
	v_mfma_f32_32x32x16_bf16 v[66:81], v[132:135], v[236:239], v[66:81]
	v_add_f32_e32 v226, v226, v143
	v_fma_f32 v145, v145, s82, v230
	v_exp_f32_e32 v145, v145
	v_add_f32_e32 v226, v226, v144
	v_fma_f32 v146, v146, s82, v230
	v_exp_f32_e32 v146, v146
	s_waitcnt lgkmcnt(4)
; #define LAS __attribute__((address_space(3)))
; DI int crow(int r, int hi) { return (r & 3) + 8 * (r >> 2) + 4 * hi; }
; #define SB() __builtin_amdgcn_sched_barrier(0)
; DI void phase_attn(int wid0, const Params& p, int L, unsigned char* lds, bool dry) {
;     ...
;                 float ps = 0.f;
; #pragma unroll
;                 for (int r = 0; r < 16; ++r) { p0[r] = __builtin_amdgcn_exp2f(p0[r] - mn); ps += p0[r]; }
;                 { auto rr = __builtin_amdgcn_permlane32_swap(__float_as_uint(ps), __float_as_uint(ps), false, false); ps = __uint_as_float(rr[0]) + __uint_as_float(rr[1]); }
;                 l_reg = l_reg * alpha + ps;
;                 __builtin_amdgcn_sched_barrier(0);
;                 bf16x8 pa0, pa1;
;     ...
;                 PK4(p0, 0, pa0); PK4(p0, 8, pa1);
;     ...
;                 __builtin_amdgcn_sched_barrier(0);
;                 if (__any(alpha < 1.f)) {
;                     if (hi == 0) al_l[r32] = alpha;
;                     asm volatile("s_waitcnt lgkmcnt(0)" ::: "memory");
;                     float ar[16];
; #pragma unroll
;                     for (int r = 0; r < 16; ++r) ar[r] = al_l[crow(r, hi)];
; #pragma unroll
;                     for (int d = 0; d < 8; ++d)
; #pragma unroll
;                         for (int r = 0; r < 16; ++r) o[d][r] *= ar[r];
;                 }
;                 __builtin_amdgcn_sched_barrier(0);
;                 LAS unsigned char* vbp = ldsl + 65536 + (t & 1) * 32768 + 16384 + v_rd_base(lane);
;                 __builtin_amdgcn_s_setprio(1);
;     ...
;                 {
;                     s16x4 a0, a1, a2, a3, b0_, b1_, b2_, b3_;
;                     PV_RD(0, a0, a1, a2, a3); SB();
;                     PV_RD(1, b0_, b1_, b2_, b3_); SB(); PV_MM(0, a0, a1, a2, a3); SB();
;                     PV_RD(2, a0, a1, a2, a3); SB(); PV_MM(1, b0_, b1_, b2_, b3_); SB();
;                     PV_RD(3, b0_, b1_, b2_, b3_); SB(); PV_MM(2, a0, a1, a2, a3); SB();
;                     PV_RD(4, a0, a1, a2, a3); SB(); PV_MM(3, b0_, b1_, b2_, b3_); SB();
;                     PV_RD(5, b0_, b1_, b2_, b3_); SB(); PV_MM(4, a0, a1, a2, a3); SB();
;                     PV_RD(6, a0, a1, a2, a3); SB(); PV_MM(5, b0_, b1_, b2_, b3_); SB();
;                     PV_RD(7, b0_, b1_, b2_, b3_); SB(); PV_MM(6, a0, a1, a2, a3); SB();
;                     PV_MM(7, b0_, b1_, b2_, b3_); SB();
;                 }
	v_mfma_f32_32x32x16_bf16 v[66:81], v[136:139], v[240:243], v[66:81]
	v_add_f32_e32 v226, v226, v145
	v_fma_f32 v147, v147, s82, v230
	v_exp_f32_e32 v147, v147
	v_add_f32_e32 v226, v226, v146
	v_fma_f32 v148, v148, s82, v230
	v_exp_f32_e32 v148, v148
	ds_read_b64_tr_b16 v[236:237], v0 offset:18944
	ds_read_b64_tr_b16 v[238:239], v0 offset:23040
	ds_read_b64_tr_b16 v[240:241], v0 offset:27136
	ds_read_b64_tr_b16 v[242:243], v0 offset:31232
	s_waitcnt lgkmcnt(6)
	v_mfma_f32_32x32x16_bf16 v[50:65], v[132:135], v[216:219], v[50:65]
	v_add_f32_e32 v226, v226, v147
	v_fma_f32 v149, v149, s82, v230
	v_exp_f32_e32 v149, v149
	v_add_f32_e32 v226, v226, v148
	v_fma_f32 v150, v150, s82, v230
	v_exp_f32_e32 v150, v150
	s_waitcnt lgkmcnt(4)
	v_mfma_f32_32x32x16_bf16 v[50:65], v[136:139], v[220:223], v[50:65]
	v_add_f32_e32 v226, v226, v149
	v_fma_f32 v151, v151, s82, v230
	v_exp_f32_e32 v151, v151
	v_add_f32_e32 v226, v226, v150
	v_fma_f32 v152, v152, s82, v230
	ds_read_b64_tr_b16 v[216:217], v0 offset:19456
	ds_read_b64_tr_b16 v[218:219], v0 offset:23552
	ds_read_b64_tr_b16 v[220:221], v0 offset:27648
	ds_read_b64_tr_b16 v[222:223], v0 offset:31744
	s_waitcnt lgkmcnt(6)
	v_mfma_f32_32x32x16_bf16 v[34:49], v[132:135], v[236:239], v[34:49]
	v_exp_f32_e32 v152, v152
	v_add_f32_e32 v226, v226, v151
	v_fma_f32 v153, v153, s82, v230
	v_exp_f32_e32 v153, v153
	s_waitcnt lgkmcnt(4)
	v_mfma_f32_32x32x16_bf16 v[34:49], v[136:139], v[240:243], v[34:49]
	v_add_f32_e32 v226, v226, v152
	v_fma_f32 v154, v154, s82, v230
	v_exp_f32_e32 v154, v154
	v_add_f32_e32 v226, v226, v153
	v_fma_f32 v155, v155, s82, v230
	ds_read_b64_tr_b16 v[236:237], v0 offset:19968
	ds_read_b64_tr_b16 v[238:239], v0 offset:24064
	ds_read_b64_tr_b16 v[240:241], v0 offset:28160
	ds_read_b64_tr_b16 v[242:243], v0 offset:32256
	s_waitcnt lgkmcnt(6)
	v_mfma_f32_32x32x16_bf16 v[18:33], v[132:135], v[216:219], v[18:33]
	v_exp_f32_e32 v155, v155
	v_add_f32_e32 v226, v226, v154
	v_exp_f32_e32 v227, v227
	v_add_f32_e32 v228, v226, v155
	s_waitcnt lgkmcnt(4)
	v_mfma_f32_32x32x16_bf16 v[18:33], v[136:139], v[220:223], v[18:33]
	v_cndmask_b32_e64 v227, v227, 1.0, vcc
	v_mov_b32_e32 v229, v228
	v_cvt_pk_bf16_f32 v156, v140, v141
	v_cvt_pk_bf16_f32 v157, v142, v143
	v_cvt_pk_bf16_f32 v158, v144, v145
	v_cvt_pk_bf16_f32 v159, v146, v147
	s_waitcnt lgkmcnt(2)
	v_mfma_f32_32x32x16_bf16 v[2:17], v[132:135], v[236:239], v[2:17]
	v_cvt_pk_bf16_f32 v160, v148, v149
	v_cvt_pk_bf16_f32 v161, v150, v151
	v_cvt_pk_bf16_f32 v162, v152, v153
	v_cvt_pk_bf16_f32 v163, v154, v155
	v_permlane32_swap_b32_e32 v228, v229
	v_permlane32_swap_b32_e32 v156, v158
	s_waitcnt lgkmcnt(0)
	v_mfma_f32_32x32x16_bf16 v[2:17], v[136:139], v[240:243], v[2:17]
	v_permlane32_swap_b32_e32 v157, v159
	v_permlane32_swap_b32_e32 v160, v162
	v_permlane32_swap_b32_e32 v161, v163
	v_add_f32_e32 v228, v228, v229
	v_fmac_f32_e32 v228, v130, v227
	v_cmp_gt_f32_e32 vcc, 1.0, v227
	s_cbranch_vccz .Lattn_norescale
	s_and_saveexec_b64 s[80:81], s[8:9]
	ds_write_b32 v196, v227 offset:128
	s_or_b64 exec, exec, s[80:81]
	s_waitcnt lgkmcnt(0)
	ds_read_b128 v[152:155], v214 offset:224
	ds_read_b128 v[148:151], v214 offset:192
	ds_read_b128 v[144:147], v214 offset:160
	ds_read_b128 v[140:143], v214 offset:128
	s_waitcnt lgkmcnt(0)
	v_pk_mul_f32 v[126:127], v[126:127], v[152:153]
	v_pk_mul_f32 v[122:123], v[122:123], v[148:149]
	v_pk_mul_f32 v[118:119], v[118:119], v[144:145]
	v_pk_mul_f32 v[128:129], v[128:129], v[154:155]
	v_pk_mul_f32 v[124:125], v[124:125], v[150:151]
	v_pk_mul_f32 v[120:121], v[120:121], v[146:147]
	v_pk_mul_f32 v[116:117], v[116:117], v[142:143]
	v_pk_mul_f32 v[114:115], v[114:115], v[140:141]
	v_pk_mul_f32 v[110:111], v[110:111], v[152:153]
	v_pk_mul_f32 v[106:107], v[106:107], v[148:149]
	v_pk_mul_f32 v[102:103], v[102:103], v[144:145]
	v_pk_mul_f32 v[112:113], v[112:113], v[154:155]
	v_pk_mul_f32 v[108:109], v[108:109], v[150:151]
	v_pk_mul_f32 v[104:105], v[104:105], v[146:147]
	v_pk_mul_f32 v[100:101], v[100:101], v[142:143]
	v_pk_mul_f32 v[98:99], v[98:99], v[140:141]
	v_pk_mul_f32 v[94:95], v[94:95], v[152:153]
	v_pk_mul_f32 v[90:91], v[90:91], v[148:149]
	v_pk_mul_f32 v[86:87], v[86:87], v[144:145]
	v_pk_mul_f32 v[96:97], v[96:97], v[154:155]
	v_pk_mul_f32 v[92:93], v[92:93], v[150:151]
	v_pk_mul_f32 v[88:89], v[88:89], v[146:147]
	v_pk_mul_f32 v[84:85], v[84:85], v[142:143]
	v_pk_mul_f32 v[82:83], v[82:83], v[140:141]
	v_pk_mul_f32 v[78:79], v[78:79], v[152:153]
	v_pk_mul_f32 v[74:75], v[74:75], v[148:149]
	v_pk_mul_f32 v[70:71], v[70:71], v[144:145]
	v_pk_mul_f32 v[80:81], v[80:81], v[154:155]
	v_pk_mul_f32 v[76:77], v[76:77], v[150:151]
	v_pk_mul_f32 v[72:73], v[72:73], v[146:147]
	v_pk_mul_f32 v[68:69], v[68:69], v[142:143]
	v_pk_mul_f32 v[66:67], v[66:67], v[140:141]
	v_pk_mul_f32 v[62:63], v[62:63], v[152:153]
	v_pk_mul_f32 v[58:59], v[58:59], v[148:149]
	v_pk_mul_f32 v[54:55], v[54:55], v[144:145]
	v_pk_mul_f32 v[64:65], v[64:65], v[154:155]
	v_pk_mul_f32 v[60:61], v[60:61], v[150:151]
	v_pk_mul_f32 v[56:57], v[56:57], v[146:147]
	v_pk_mul_f32 v[52:53], v[52:53], v[142:143]
	v_pk_mul_f32 v[50:51], v[50:51], v[140:141]
	v_pk_mul_f32 v[46:47], v[46:47], v[152:153]
	v_pk_mul_f32 v[42:43], v[42:43], v[148:149]
	v_pk_mul_f32 v[38:39], v[38:39], v[144:145]
	v_pk_mul_f32 v[48:49], v[48:49], v[154:155]
	v_pk_mul_f32 v[44:45], v[44:45], v[150:151]
	v_pk_mul_f32 v[40:41], v[40:41], v[146:147]
	v_pk_mul_f32 v[36:37], v[36:37], v[142:143]
	v_pk_mul_f32 v[34:35], v[34:35], v[140:141]
	v_pk_mul_f32 v[30:31], v[30:31], v[152:153]
	v_pk_mul_f32 v[26:27], v[26:27], v[148:149]
	v_pk_mul_f32 v[22:23], v[22:23], v[144:145]
	v_pk_mul_f32 v[32:33], v[32:33], v[154:155]
	v_pk_mul_f32 v[28:29], v[28:29], v[150:151]
	v_pk_mul_f32 v[24:25], v[24:25], v[146:147]
	v_pk_mul_f32 v[20:21], v[20:21], v[142:143]
	v_pk_mul_f32 v[18:19], v[18:19], v[140:141]
	v_pk_mul_f32 v[14:15], v[14:15], v[152:153]
	v_pk_mul_f32 v[10:11], v[10:11], v[148:149]
	v_pk_mul_f32 v[6:7], v[6:7], v[144:145]
	v_pk_mul_f32 v[16:17], v[16:17], v[154:155]
	v_pk_mul_f32 v[12:13], v[12:13], v[150:151]
	v_pk_mul_f32 v[8:9], v[8:9], v[146:147]
	v_pk_mul_f32 v[4:5], v[4:5], v[142:143]
	v_pk_mul_f32 v[2:3], v[2:3], v[140:141]
; #define LAS __attribute__((address_space(3)))
; DI int v_rd_base(int lane) { return ((lane & 3) << 3) | (((lane >> 2) & 3) << 6) | (((lane >> 4) & 1) << 5) | (((lane >> 5) & 1) << 8); }
; #define PV_RD(D0, L0, H0, L1, H1) L0 = TRB(v_rd_off(D0, 0, 0)); H0 = TRB(v_rd_off(D0, 0, 1)); L1 = TRB(v_rd_off(D0, 1, 0)); H1 = TRB(v_rd_off(D0, 1, 1))
; #define PV_MM(D0, L0, H0, L1, H1) o[D0] = MFMA32(pa0, PK8(L0, H0), o[D0]); o[D0] = MFMA32(pa1, PK8(L1, H1), o[D0])
; #define SB() __builtin_amdgcn_sched_barrier(0)
; DI void phase_attn(int wid0, const Params& p, int L, unsigned char* lds, bool dry) {
;     ...
;         for (int t = 0; t < ntiles; ++t) {
;             asm volatile("s_waitcnt vmcnt(0) lgkmcnt(0)" ::: "memory"); __builtin_amdgcn_s_barrier(); asm volatile("" ::: "memory");
;             if (t + 1 < ntiles) attn_stage(kh_ + (size_t)(b * 4096 + 32 * t) * 2048, vh_ + (size_t)(b * 4096 + 32 * t) * 2048, koff, voff, ldsl + 65536 + ((t + 1) & 1) * 32768, wid);
;     ...
;                 LAS unsigned char* vbp = ldsl + 65536 + (t & 1) * 32768 + 16384 + v_rd_base(lane);
;                 __builtin_amdgcn_s_setprio(1);
;     ...
;                 {
;                     s16x4 a0, a1, a2, a3, b0_, b1_, b2_, b3_;
;                     PV_RD(0, a0, a1, a2, a3); SB();
;                     PV_RD(1, b0_, b1_, b2_, b3_); SB(); PV_MM(0, a0, a1, a2, a3); SB();
;                     PV_RD(2, a0, a1, a2, a3); SB(); PV_MM(1, b0_, b1_, b2_, b3_); SB();
;                     PV_RD(3, b0_, b1_, b2_, b3_); SB(); PV_MM(2, a0, a1, a2, a3); SB();
;                     PV_RD(4, a0, a1, a2, a3); SB(); PV_MM(3, b0_, b1_, b2_, b3_); SB();
;                     PV_RD(5, b0_, b1_, b2_, b3_); SB(); PV_MM(4, a0, a1, a2, a3); SB();
;                     PV_RD(6, a0, a1, a2, a3); SB(); PV_MM(5, b0_, b1_, b2_, b3_); SB();
;                     PV_RD(7, b0_, b1_, b2_, b3_); SB(); PV_MM(6, a0, a1, a2, a3); SB();
;                     PV_MM(7, b0_, b1_, b2_, b3_); SB();
;                 }
;     ...
;                 __builtin_amdgcn_s_setprio(0);
;             }
;         }
.Lattn_norescale:
	v_mov_b32_e32 v130, v228
	v_mov_b32_e32 v132, v156
	v_mov_b32_e32 v133, v157
	v_mov_b32_e32 v134, v158
	v_mov_b32_e32 v135, v159
	v_mov_b32_e32 v136, v160
	v_mov_b32_e32 v137, v161
	v_mov_b32_e32 v138, v162
	v_mov_b32_e32 v139, v163
	s_or_b32 s100, s100, 0x100
	s_branch .LBB0_111
.Lattn_skip:
	s_bitcmp1_b32 s100, 8
	s_cbranch_scc0 .LBB0_111
.Lattn_pvplain:
	v_add_u32_e32 v0, s101, v212
	s_setprio 1
	ds_read_b64_tr_b16 v[140:141], v0 offset:16384
	ds_read_b64_tr_b16 v[142:143], v0 offset:20480
	ds_read_b64_tr_b16 v[144:145], v0 offset:24576
	ds_read_b64_tr_b16 v[146:147], v0 offset:28672
	ds_read_b64_tr_b16 v[148:149], v0 offset:16896
	ds_read_b64_tr_b16 v[150:151], v0 offset:20992
	ds_read_b64_tr_b16 v[152:153], v0 offset:25088
	ds_read_b64_tr_b16 v[154:155], v0 offset:29184
	s_waitcnt lgkmcnt(6)
	v_mfma_f32_32x32x16_bf16 v[114:129], v[132:135], v[140:143], v[114:129]
	s_waitcnt lgkmcnt(4)
	v_mfma_f32_32x32x16_bf16 v[114:129], v[136:139], v[144:147], v[114:129]
	ds_read_b64_tr_b16 v[140:141], v0 offset:17408
	ds_read_b64_tr_b16 v[142:143], v0 offset:21504
	ds_read_b64_tr_b16 v[144:145], v0 offset:25600
	ds_read_b64_tr_b16 v[146:147], v0 offset:29696
	s_waitcnt lgkmcnt(6)
	v_mfma_f32_32x32x16_bf16 v[98:113], v[132:135], v[148:151], v[98:113]
	s_waitcnt lgkmcnt(4)
	v_mfma_f32_32x32x16_bf16 v[98:113], v[136:139], v[152:155], v[98:113]
	ds_read_b64_tr_b16 v[148:149], v0 offset:17920
	ds_read_b64_tr_b16 v[150:151], v0 offset:22016
	ds_read_b64_tr_b16 v[152:153], v0 offset:26112
	ds_read_b64_tr_b16 v[154:155], v0 offset:30208
	s_waitcnt lgkmcnt(6)
	v_mfma_f32_32x32x16_bf16 v[82:97], v[132:135], v[140:143], v[82:97]
	s_waitcnt lgkmcnt(4)
	v_mfma_f32_32x32x16_bf16 v[82:97], v[136:139], v[144:147], v[82:97]
	ds_read_b64_tr_b16 v[140:141], v0 offset:18432
	ds_read_b64_tr_b16 v[142:143], v0 offset:22528
	ds_read_b64_tr_b16 v[144:145], v0 offset:26624
	ds_read_b64_tr_b16 v[146:147], v0 offset:30720
	s_waitcnt lgkmcnt(6)
	v_mfma_f32_32x32x16_bf16 v[66:81], v[132:135], v[148:151], v[66:81]
	s_waitcnt lgkmcnt(4)
	v_mfma_f32_32x32x16_bf16 v[66:81], v[136:139], v[152:155], v[66:81]
	ds_read_b64_tr_b16 v[148:149], v0 offset:18944
	ds_read_b64_tr_b16 v[150:151], v0 offset:23040
	ds_read_b64_tr_b16 v[152:153], v0 offset:27136
	ds_read_b64_tr_b16 v[154:155], v0 offset:31232
	s_waitcnt lgkmcnt(6)
	v_mfma_f32_32x32x16_bf16 v[50:65], v[132:135], v[140:143], v[50:65]
	s_waitcnt lgkmcnt(4)
	v_mfma_f32_32x32x16_bf16 v[50:65], v[136:139], v[144:147], v[50:65]
	ds_read_b64_tr_b16 v[140:141], v0 offset:19456
	ds_read_b64_tr_b16 v[142:143], v0 offset:23552
	ds_read_b64_tr_b16 v[144:145], v0 offset:27648
	ds_read_b64_tr_b16 v[146:147], v0 offset:31744
	s_waitcnt lgkmcnt(6)
	v_mfma_f32_32x32x16_bf16 v[34:49], v[132:135], v[148:151], v[34:49]
	s_waitcnt lgkmcnt(4)
	v_mfma_f32_32x32x16_bf16 v[34:49], v[136:139], v[152:155], v[34:49]
	ds_read_b64_tr_b16 v[148:149], v0 offset:19968
	ds_read_b64_tr_b16 v[150:151], v0 offset:24064
	ds_read_b64_tr_b16 v[152:153], v0 offset:28160
	ds_read_b64_tr_b16 v[154:155], v0 offset:32256
	s_waitcnt lgkmcnt(6)
	v_mfma_f32_32x32x16_bf16 v[18:33], v[132:135], v[140:143], v[18:33]
	s_waitcnt lgkmcnt(4)
	v_mfma_f32_32x32x16_bf16 v[18:33], v[136:139], v[144:147], v[18:33]
	s_waitcnt lgkmcnt(2)
	v_mfma_f32_32x32x16_bf16 v[2:17], v[132:135], v[148:151], v[2:17]
	s_waitcnt lgkmcnt(0)
	v_mfma_f32_32x32x16_bf16 v[2:17], v[136:139], v[152:155], v[2:17]
	s_setprio 0
	s_andn2_b32 s100, s100, 0x100
	s_bitcmp1_b32 s100, 9
	s_cbranch_scc1 .LBB0_113
.LBB0_111:
	s_and_b32 s82, s100, 3
	s_lshl_b32 s101, s82, 15
	s_add_i32 s82, s82, 1
	s_cmp_eq_u32 s82, 3
	s_cselect_b32 s82, 0, s82
	s_andn2_b32 s100, s100, 3
	s_or_b32 s100, s100, s82
	s_add_i32 s66, s66, 0x8000
	s_sub_i32 s39, s39, 32
	s_add_i32 s7, s7, 32
	s_cmp_eq_u32 s6, s67
	s_cbranch_scc1 .Lattn_exit
	s_mov_b32 s69, s67
	s_branch .LBB0_99
.Lattn_exit:
	s_bitcmp1_b32 s100, 8
	s_cbranch_scc0 .LBB0_113
	s_or_b32 s100, s100, 0x200
	s_branch .Lattn_pvplain

; DI void phase_attn(int wid0, const Params& p, int L, unsigned char* lds, bool dry) {
;     ...
;         __syncthreads();
;     }
; }
.LBB0_128:
	v_mov_b64_e32 v[164:165], 0x400
	v_mov_b64_e32 v[166:167], 0x3ff
	v_mov_b64_e32 v[168:169], 0xc00
	v_mov_b64_e32 v[170:171], 0xbff
	v_mov_b64_e32 v[172:173], 0x200
	v_mov_b64_e32 v[174:175], 0x1ff
	v_mov_b32_e32 v232, v1
	v_mov_b32_e32 v233, v1
	v_mov_b32_e32 v234, v1
	v_mov_b32_e32 v235, v1
	s_mov_b64 s[4:5], 0
	s_movk_i32 s40, 0x7fff
	v_readlane_b32 s41, v245, 48

; #define LAS __attribute__((address_space(3)))
; __global__ void __launch_bounds__(512) mega(Params p_arg) {
;     extern __shared__ __attribute__((aligned(16))) unsigned char lds[];
;     cg::grid_group grid = cg::this_grid();
;     const int ph_lo = p_arg.ph_lo, ph_hi = p_arg.ph_hi;
;     if (ph_lo < 0) grid.sync();
;     volatile LAS unsigned* xbst = (volatile LAS unsigned*)(LAS unsigned char*)(lds + LDS_BYTES - 16);
	.amdhsa_kernel _Z4mega6Params
		.amdhsa_group_segment_fixed_size 16384
		.amdhsa_private_segment_fixed_size 0
		.amdhsa_kernarg_size 392
		.amdhsa_user_sgpr_count 2
		.amdhsa_user_sgpr_dispatch_ptr 0
		.amdhsa_user_sgpr_queue_ptr 0
		.amdhsa_user_sgpr_kernarg_segment_ptr 1
		.amdhsa_user_sgpr_dispatch_id 0
		.amdhsa_user_sgpr_kernarg_preload_length 0
		.amdhsa_user_sgpr_kernarg_preload_offset 0
		.amdhsa_user_sgpr_private_segment_size 0
		.amdhsa_uses_dynamic_stack 0
		.amdhsa_enable_private_segment 0
		.amdhsa_system_sgpr_workgroup_id_x 1
		.amdhsa_system_sgpr_workgroup_id_y 0
		.amdhsa_system_sgpr_workgroup_id_z 0
		.amdhsa_system_sgpr_workgroup_info 0
		.amdhsa_system_vgpr_workitem_id 2
		.amdhsa_next_free_vgpr 256
		.amdhsa_next_free_sgpr 102
		.amdhsa_accum_offset 256
		.amdhsa_reserve_vcc 1
		.amdhsa_float_round_mode_32 0
		.amdhsa_float_round_mode_16_64 0
		.amdhsa_float_denorm_mode_32 3
		.amdhsa_float_denorm_mode_16_64 3
		.amdhsa_dx10_clamp 1
		.amdhsa_ieee_mode 1
		.amdhsa_fp16_overflow 0
		.amdhsa_tg_split 0
		.amdhsa_exception_fp_ieee_invalid_op 0
		.amdhsa_exception_fp_denorm_src 0
		.amdhsa_exception_fp_ieee_div_zero 0
		.amdhsa_exception_fp_ieee_overflow 0
		.amdhsa_exception_fp_ieee_underflow 0
		.amdhsa_exception_fp_ieee_inexact 0
		.amdhsa_exception_int_div_zero 0
	.end_amdhsa_kernel

; #define LAS __attribute__((address_space(3)))
; __global__ void __launch_bounds__(512) mega(Params p_arg) {
;     extern __shared__ __attribute__((aligned(16))) unsigned char lds[];
;     cg::grid_group grid = cg::this_grid();
;     const int ph_lo = p_arg.ph_lo, ph_hi = p_arg.ph_hi;
;     if (ph_lo < 0) grid.sync();
;     volatile LAS unsigned* xbst = (volatile LAS unsigned*)(LAS unsigned char*)(lds + LDS_BYTES - 16);
amdhsa.kernels:
  - .agpr_count:     0
    .args:
      - .offset:         0
        .size:           136
        .value_kind:     by_value
      - .offset:         136
        .size:           4
        .value_kind:     hidden_block_count_x
      - .offset:         140
        .size:           4
        .value_kind:     hidden_block_count_y
      - .offset:         144
        .size:           4
        .value_kind:     hidden_block_count_z
      - .offset:         148
        .size:           2
        .value_kind:     hidden_group_size_x
      - .offset:         150
        .size:           2
        .value_kind:     hidden_group_size_y
      - .offset:         152
        .size:           2
        .value_kind:     hidden_group_size_z
      - .offset:         154
        .size:           2
        .value_kind:     hidden_remainder_x
      - .offset:         156
        .size:           2
        .value_kind:     hidden_remainder_y
      - .offset:         158
        .size:           2
        .value_kind:     hidden_remainder_z
      - .offset:         176
        .size:           8
        .value_kind:     hidden_global_offset_x
      - .offset:         184
        .size:           8
        .value_kind:     hidden_global_offset_y
      - .offset:         192
        .size:           8
        .value_kind:     hidden_global_offset_z
      - .offset:         200
        .size:           2
        .value_kind:     hidden_grid_dims
      - .offset:         224
        .size:           8
        .value_kind:     hidden_multigrid_sync_arg
      - .offset:         256
        .size:           4
        .value_kind:     hidden_dynamic_lds_size
    .group_segment_fixed_size: 16384
    .kernarg_segment_align: 8
    .kernarg_segment_size: 392
    .language:       OpenCL C
    .language_version:
      - 2
      - 0
    .max_flat_workgroup_size: 512
    .name:           _Z4mega6Params
    .private_segment_fixed_size: 0
    .sgpr_count:     108
    .sgpr_spill_count: 207
    .symbol:         _Z4mega6Params.kd
    .uniform_work_group_size: 1
    .uses_dynamic_stack: false
    .vgpr_count:     256
    .vgpr_spill_count: 0
    .wavefront_size: 64
